# GU GEMM: next-unit row-index gathers hoisted to unit start; per-unit vmcnt(0) drain removed
# speedup vs baseline: 1.0059x; 1.0042x over previous
.LBB0_1242:
	s_mov_b64 s[10:11], 0x80
	s_add_i32 m0, s28, 0x18000
	v_lshl_add_u64 v[6:7], v[6:7], 0, s[10:11]
	s_waitcnt vmcnt(2)
	s_barrier
	global_load_lds_dwordx4 v[6:7], off
	v_lshl_add_u64 v[2:3], v[2:3], 0, s[10:11]
	s_add_i32 m0, s28, 0x1a000
	s_add_i32 s38, s28, 0x8000
	s_add_i32 s39, s28, 0xa000
	global_load_lds_dwordx4 v[2:3], off
	v_lshl_add_u64 v[0:1], v[0:1], 0, s[10:11]
	s_mov_b32 m0, s38
	s_add_u32 s12, s22, 0x20080
	global_load_lds_dwordx4 v[0:1], off
	v_lshl_add_u64 v[0:1], v[4:5], 0, s[10:11]
	s_mov_b32 m0, s39
	s_addc_u32 s13, s23, 0
	global_load_lds_dwordx4 v[0:1], off
	s_add_i32 m0, s28, 0x1c000
	v_lshl_add_u64 v[0:1], s[12:13], 0, v[162:163]
	global_load_lds_dwordx4 v[0:1], off
	v_lshl_add_u64 v[0:1], s[12:13], 0, v[160:161]
	s_add_i32 m0, s28, 0x1e000
	v_and_b32_e32 v2, 48, v8
	global_load_lds_dwordx4 v[0:1], off
	v_and_b32_e32 v0, 15, v8
	v_or_b32_e32 v1, s91, v0
	v_lshlrev_b32_e32 v3, 6, v1
	s_movk_i32 s6, 0x3c0
	v_and_or_b32 v3, v3, s6, v2
	v_lshl_or_b32 v0, v0, 6, v2
	v_lshlrev_b32_e32 v2, 2, v8
	v_lshlrev_b32_e32 v1, 2, v1
	v_and_b32_e32 v2, 32, v2
	v_and_b32_e32 v1, 32, v1
	v_readlane_b32 s6, v253, 38
	v_bitop3_b32 v176, v0, s74, v2 bitop3:0xde
	s_waitcnt vmcnt(6)
	s_cmpk_lt_u32 s76, 0x100
	v_bitop3_b32 v1, v3, s6, v1 bitop3:0xde
	s_cselect_b64 s[12:13], -1, 0
	s_add_u32 s40, s66, 0x16000080
	v_add_u32_e32 v0, 0, v176
	s_mov_b32 s69, s7
	s_addc_u32 s41, s67, 0
	v_add_u32_e32 v177, 0x10000, v0
	v_add_u32_e32 v178, 0x14000, v0
	v_add_u32_e32 v179, 0, v1
	s_mov_b32 s14, 0x3d000000
	s_movk_i32 s42, 0xb00
	s_add_i32 s43, s28, 0xc000
	s_add_i32 s44, s28, 0xe000
	s_mov_b32 s45, 0
	s_barrier
	v_add_u32_e32 v247, s33, v174
	v_lshrrev_b32_e32 v252, 7, v247
	v_bfe_u32 v247, v247, 2, 4
	v_lshl_add_u32 v247, v252, 4, v247
	v_add_u32_e32 v252, 64, v247
	s_branch .LBB0_1245

.LBB0_1247:
	s_ashr_i32 s17, s16, 31
	s_lshl_b64 s[20:21], s[16:17], 18
	s_add_u32 s20, s88, s20
	s_addc_u32 s21, s89, s21
	s_and_b64 s[24:25], s[18:19], exec
	s_cselect_b32 s17, s21, s23
	s_cselect_b32 s50, s20, s22
	s_lshl_b32 s51, s46, 8
	s_or_b32 s52, s51, 0x80
	s_add_u32 s53, s22, 0x100
	v_mov_b64_e32 v[32:33], 0
	v_mov_b64_e32 v[34:35], 0
	v_mov_b64_e32 v[36:37], 0
	v_mov_b64_e32 v[38:39], 0
	v_mov_b64_e32 v[40:41], 0
	v_mov_b64_e32 v[42:43], 0
	v_mov_b64_e32 v[44:45], 0
	v_mov_b64_e32 v[46:47], 0
	v_mov_b64_e32 v[48:49], 0
	v_mov_b64_e32 v[50:51], 0
	v_mov_b64_e32 v[52:53], 0
	v_mov_b64_e32 v[54:55], 0
	v_mov_b64_e32 v[56:57], 0
	v_mov_b64_e32 v[58:59], 0
	v_mov_b64_e32 v[60:61], 0
	v_mov_b64_e32 v[62:63], 0
	v_mov_b64_e32 v[64:65], 0
	v_mov_b64_e32 v[66:67], 0
	v_mov_b64_e32 v[68:69], 0
	v_mov_b64_e32 v[70:71], 0
	v_mov_b64_e32 v[72:73], 0
	v_mov_b64_e32 v[74:75], 0
	v_mov_b64_e32 v[76:77], 0
	v_mov_b64_e32 v[78:79], 0
	v_mov_b64_e32 v[80:81], 0
	v_mov_b64_e32 v[82:83], 0
	v_mov_b64_e32 v[84:85], 0
	v_mov_b64_e32 v[86:87], 0
	v_mov_b64_e32 v[88:89], 0
	v_mov_b64_e32 v[90:91], 0
	v_mov_b64_e32 v[92:93], 0
	v_mov_b64_e32 v[94:95], 0
	v_mov_b64_e32 v[96:97], 0
	v_mov_b64_e32 v[98:99], 0
	v_mov_b64_e32 v[100:101], 0
	v_mov_b64_e32 v[102:103], 0
	v_mov_b64_e32 v[104:105], 0
	v_mov_b64_e32 v[106:107], 0
	v_mov_b64_e32 v[108:109], 0
	v_mov_b64_e32 v[110:111], 0
	v_mov_b64_e32 v[112:113], 0
	v_mov_b64_e32 v[114:115], 0
	v_mov_b64_e32 v[116:117], 0
	v_mov_b64_e32 v[118:119], 0
	v_mov_b64_e32 v[120:121], 0
	v_mov_b64_e32 v[122:123], 0
	v_mov_b64_e32 v[124:125], 0
	v_mov_b64_e32 v[126:127], 0
	v_mov_b64_e32 v[128:129], 0
	v_mov_b64_e32 v[130:131], 0
	v_mov_b64_e32 v[132:133], 0
	v_mov_b64_e32 v[134:135], 0
	v_mov_b64_e32 v[136:137], 0
	v_mov_b64_e32 v[138:139], 0
	v_mov_b64_e32 v[140:141], 0
	v_mov_b64_e32 v[142:143], 0
	v_mov_b64_e32 v[144:145], 0
	v_mov_b64_e32 v[146:147], 0
	v_mov_b64_e32 v[148:149], 0
	v_mov_b64_e32 v[150:151], 0
	v_mov_b64_e32 v[152:153], 0
	v_mov_b64_e32 v[154:155], 0
	v_mov_b64_e32 v[156:157], 0
	v_mov_b64_e32 v[158:159], 0
	s_addc_u32 s56, s23, 0
	s_mov_b32 s57, -2
	s_mov_b64 s[22:23], 0
	s_and_b64 vcc, exec, s[18:19]
	s_cbranch_vccz .Lgu_noidx
	v_add_lshl_u32 v248, v247, s51, 2
	v_add_lshl_u32 v249, v252, s51, 2
	v_add_lshl_u32 v250, v247, s52, 2
	v_add_lshl_u32 v251, v252, s52, 2
	global_load_dword v248, v248, s[0:1]
	global_load_dword v249, v249, s[0:1]
	global_load_dword v250, v250, s[0:1]
	global_load_dword v251, v251, s[0:1]
.Lgu_noidx:
.LBB0_1248:
	ds_read_b128 v[16:19], v177
	ds_read_b128 v[20:23], v177 offset:1024
	ds_read_b128 v[24:27], v177 offset:2048
	ds_read_b128 v[28:31], v177 offset:3072
	ds_read_b128 v[0:3], v178
	ds_read_b128 v[4:7], v178 offset:1024
	ds_read_b128 v[8:11], v178 offset:2048
	ds_read_b128 v[12:15], v178 offset:3072
	s_cmp_eq_u32 s57, 4
	s_cselect_b64 s[26:27], -1, 0
	s_add_u32 s24, s40, s22
	s_addc_u32 s25, s41, s23
	s_mov_b32 m0, s43
	ds_read_b128 v[180:183], v179
	ds_read_b128 v[184:187], v179 offset:1024
	ds_read_b128 v[188:191], v179 offset:2048
	ds_read_b128 v[192:195], v179 offset:3072
	ds_read_b128 v[196:199], v179 offset:4096
	ds_read_b128 v[200:203], v179 offset:5120
	ds_read_b128 v[204:207], v179 offset:6144
	ds_read_b128 v[208:211], v179 offset:7168
	global_load_lds_dwordx4 v168, s[24:25]
	s_mov_b32 m0, s44
	s_nop 0
	global_load_lds_dwordx4 v166, s[24:25]
	s_waitcnt vmcnt(8)
	s_waitcnt lgkmcnt(0)
	s_barrier
	s_setprio 1
	s_waitcnt lgkmcnt(0)
	v_mfma_f32_16x16x128_f8f6f4 v[156:159], v[16:23], v[180:187], v[156:159]
	v_mfma_f32_16x16x128_f8f6f4 v[152:155], v[24:31], v[180:187], v[152:155]
	v_mfma_f32_16x16x128_f8f6f4 v[140:143], v[16:23], v[188:195], v[140:143]
	v_mfma_f32_16x16x128_f8f6f4 v[136:139], v[24:31], v[188:195], v[136:139]
	v_mfma_f32_16x16x128_f8f6f4 v[124:127], v[16:23], v[196:203], v[124:127]
	v_mfma_f32_16x16x128_f8f6f4 v[120:123], v[24:31], v[196:203], v[120:123]
	v_mfma_f32_16x16x128_f8f6f4 v[108:111], v[16:23], v[204:211], v[108:111]
	v_mfma_f32_16x16x128_f8f6f4 v[104:107], v[24:31], v[204:211], v[104:107]
	v_mfma_f32_16x16x128_f8f6f4 v[148:151], v[0:7], v[180:187], v[148:151]
	v_mfma_f32_16x16x128_f8f6f4 v[144:147], v[8:15], v[180:187], v[144:147]
	v_mfma_f32_16x16x128_f8f6f4 v[132:135], v[0:7], v[188:195], v[132:135]
	v_mfma_f32_16x16x128_f8f6f4 v[128:131], v[8:15], v[188:195], v[128:131]
	v_mfma_f32_16x16x128_f8f6f4 v[116:119], v[0:7], v[196:203], v[116:119]
	v_mfma_f32_16x16x128_f8f6f4 v[112:115], v[8:15], v[196:203], v[112:115]
	v_mfma_f32_16x16x128_f8f6f4 v[100:103], v[0:7], v[204:211], v[100:103]
	v_mfma_f32_16x16x128_f8f6f4 v[96:99], v[8:15], v[204:211], v[96:99]
	s_setprio 0
	s_barrier
	s_and_b64 s[24:25], s[18:19], s[26:27]
	s_andn2_b64 vcc, exec, s[24:25]
	s_cbranch_vccnz .LBB0_1250
	v_mov_b32_e32 v164, v174
	s_nop 0
	v_add_u32_e32 v164, s33, v164
	v_ashrrev_i32_e32 v167, 31, v164
	v_lshrrev_b32_e32 v167, 26, v167
	v_lshlrev_b32_e32 v166, 4, v164
	v_add_u32_e32 v167, v164, v167
	v_bfe_i32 v164, v164, 27, 1
	v_lshrrev_b32_e32 v164, 22, v164
	v_add_u32_e32 v164, v166, v164
	v_and_b32_e32 v164, 0xfffffc00, v164
	v_sub_u32_e32 v164, v166, v164
	v_ashrrev_i32_e32 v180, 6, v167
	v_lshrrev_b32_e32 v167, 4, v164
	v_bitop3_b32 v164, v167, v164, 32 bitop3:0x6c
	v_ashrrev_i32_e32 v168, 31, v164
	v_lshrrev_b32_e32 v168, 26, v168
	v_lshlrev_b32_e32 v167, 3, v180
	v_add_u32_e32 v181, v164, v168
	v_and_b32_e32 v167, -16, v167
	v_ashrrev_i32_e32 v168, 6, v181
	v_add_u32_e32 v166, 0x2000, v166
	v_add_u32_e32 v170, v168, v167
	v_ashrrev_i32_e32 v167, 31, v166
	v_lshrrev_b32_e32 v167, 22, v167
	v_add_u32_e32 v167, v166, v167
	v_ashrrev_i32_e32 v182, 10, v167
	v_mul_i32_i24_e32 v167, 0x400, v182
	v_sub_u32_e32 v166, v166, v167
	v_lshrrev_b32_e32 v167, 4, v166
	v_bitop3_b32 v183, v167, v166, 32 bitop3:0x6c
	v_ashrrev_i32_e32 v167, 31, v183
	v_lshrrev_b32_e32 v167, 26, v167
	v_lshlrev_b32_e32 v166, 3, v182
	v_add_u32_e32 v184, v183, v167
	v_and_b32_e32 v166, -16, v166
	v_ashrrev_i32_e32 v167, 6, v184
	v_add_u32_e32 v172, v167, v166
	v_and_b32_e32 v173, 0xc0, v181
	v_sub_u32_e32 v164, v164, v173
	v_lshlrev_b32_e32 v170, 5, v180
	v_ashrrev_i16_sdwa v164, v175, sext(v164) dst_sel:DWORD dst_unused:UNUSED_PAD src0_sel:DWORD src1_sel:BYTE_0
	v_and_b32_e32 v173, 0xc0, v184
	v_and_b32_e32 v170, 32, v170
	v_bfe_i32 v164, v164, 0, 16
	v_sub_u32_e32 v173, v183, v173
	v_lshlrev_b32_e32 v172, 5, v182
	v_add_lshl_u32 v164, v170, v164, 1
	v_ashrrev_i16_sdwa v170, v175, sext(v173) dst_sel:DWORD dst_unused:UNUSED_PAD src0_sel:DWORD src1_sel:BYTE_0
	v_and_b32_e32 v172, 32, v172
	v_bfe_i32 v170, v170, 0, 16
	v_add_lshl_u32 v172, v172, v170, 1
	v_mov_b32_e32 v167, v165
	v_lshl_add_u32 v180, v248, 10, v164
	v_lshl_add_u32 v170, v249, 10, v172
	v_lshl_add_u32 v164, v250, 10, v164
	v_lshl_add_u32 v166, v251, 10, v172
	v_mov_b64_e32 v[172:173], v[164:165]
	v_mov_b32_e32 v168, v164
	v_mov_b32_e32 v164, v180
	s_branch .LBB0_1251
